# hot GEMM loops 256B-aligned (p2align), filler s_nops pruned by hazard check in SSD hoisted windows
# baseline (speedup 1.0000x reference)
; template <int MODE>
; PH void gemm_phase(const Params& p, int layer) {
;     ...
; #pragma unroll 1
;     for (int g0 = 0; g0 < total; g0 += 2) {
.LBB0_171:
	s_barrier
	.p2align 8

; DI float bflo(unsigned u) { return __uint_as_float(u << 16); }
; DI float bfhi(unsigned u) { return __uint_as_float(u & 0xffff0000u); }
; template <int PROBE, int SONLY, int CPS>
; DI void ssd_chunk_loop(const Params& p, int layer, int b, int e, int c0, f32x4 (&h)[8], float& dtot, bool write_final) {
;     ...
;     {
;       const int nb_ = b * 2048 + ((cc + 1 < c0 + CPS) ? (cc + 1) : cc) * 64;
; #pragma unroll
;       for (int i = 0; i < 4; ++i) {
;         const int idx = tid + 256 * i, r = idx >> 4, c16 = idx & 15;
;         if (!SONLY) pc[i] = *(const u32x4*)(XBC + (size_t)(nb_ + r) * 1280 + 1024 + g * 128 + c16 * 8);
;         pb[i] = *(const u32x4*)(XBC + (size_t)(nb_ + r) * 1280 + 768 + g * 128 + c16 * 8);
;       }
; #pragma unroll
;       for (int i = 0; i < 2; ++i) {
;         const int idx = tid + 256 * i, r = idx >> 3, c8 = idx & 7;
;         px[i] = *(const u32x4*)(XBC + (size_t)(nb_ + r) * 1280 + e * 64 + c8 * 8);
;       }
;       pru = PROJ[(size_t)(nb_ + lane) * NPAD + C_DT + e];
;     }
;     uint2 dx[4], dz[4];
;     if (!SONLY)
; #pragma unroll
;     for (int qt = 0; qt < 4; ++qt) {
;       const size_t row = (size_t)(base + qt * 16 + l15);
;       const int pcol = w * 16 + quad * 4;
;       dx[qt] = *(const uint2*)(XBC + row * 1280 + e * 64 + pcol);
;       dz[qt] = *(const uint2*)(PROJ + row * NPAD + C_Z + e * 64 + pcol);
;     }
;     __syncthreads();
;     dtot += acs_s[63];
;     if (!(PROBE & 2)) {
; #pragma unroll
;     for (int i = 0; i < 2; ++i) {
;       const int idx = tid + 256 * i, r = idx >> 3, c8 = idx & 7;
;       const float dtv = dt_s[r];
;       float f[8]; unpack8v(xr[i], f);
; #pragma unroll
;       for (int j = 0; j < 8; ++j) Xt[(c8 * 8 + j) * 72 + r] = f2bf(f[j] * dtv);
;     }
;     {
;       const int q = tid & 63, ng = tid >> 6;
;       const float dte = __expf(acs_s[63] - acs_s[q]);
; #pragma unroll
;       for (int i = 0; i < 8; ++i) {
;         const uint2 v = *(const uint2*)(Bs + q * 136 + ng * 32 + i * 4);
;         Bt2[(ng * 32 + i * 4 + 0) * 72 + q] = f2bf(bflo(v.x) * dte);
;         Bt2[(ng * 32 + i * 4 + 1) * 72 + q] = f2bf(bfhi(v.x) * dte);
;         Bt2[(ng * 32 + i * 4 + 2) * 72 + q] = f2bf(bflo(v.y) * dte);
;         Bt2[(ng * 32 + i * 4 + 3) * 72 + q] = f2bf(bfhi(v.y) * dte);
;       }
;     }
.LBB0_483:
	s_or_b64 exec, exec, s[50:51]
	s_add_i32 s0, s6, s7
	s_add_i32 s1, s0, 1
	s_cmp_lt_i32 s1, s18
	s_cselect_b32 s0, s1, s0
	s_lshl_b32 s0, s0, 6
	s_add_i32 s22, s0, s13
	s_waitcnt vmcnt(0)
	v_or_b32_e32 v95, s22, v72
	v_mov_b64_e32 v[96:97], s[4:5]
	v_add_u32_e32 v0, s22, v73
	v_add_u32_e32 v4, s22, v75
	v_add_u32_e32 v8, s22, v76
	v_add_u32_e32 v12, s22, v77
	v_add_u32_e32 v16, s22, v74
	v_add_u32_e32 v20, s22, v78
	v_mad_i64_i32 v[96:97], s[0:1], v95, s97, v[96:97]
	v_mad_i64_i32 v[0:1], s[0:1], v0, s34, v[70:71]
	v_mad_i64_i32 v[4:5], s[0:1], v4, s34, v[70:71]
	v_mad_i64_i32 v[8:9], s[0:1], v8, s34, v[70:71]
	v_mad_i64_i32 v[12:13], s[0:1], v12, s34, v[70:71]
	v_mad_i64_i32 v[16:17], s[0:1], v16, s34, v[66:67]
	v_mad_i64_i32 v[20:21], s[0:1], v20, s34, v[66:67]
	v_lshl_add_u64 v[96:97], v[64:65], 1, v[96:97]
	v_add_co_u32_e64 v96, s[0:1], s16, v96
	global_load_dwordx4 v[0:3], v[0:1], off offset:1536
	s_nop 0
	v_addc_co_u32_e64 v97, s[0:1], 0, v97, s[0:1]
	global_load_dwordx4 v[4:7], v[4:5], off offset:1536
	v_lshlrev_b32_e32 v99, 16, v28
	global_load_dwordx4 v[8:11], v[8:9], off offset:1536
	v_and_b32_e32 v28, 0xffff0000, v28
	global_load_dwordx4 v[12:15], v[12:13], off offset:1536
	v_lshlrev_b32_e32 v100, 16, v29
	global_load_dwordx4 v[16:19], v[16:17], off
	v_and_b32_e32 v29, 0xffff0000, v29
	global_load_dwordx4 v[20:23], v[20:21], off
	v_lshlrev_b32_e32 v101, 16, v30
	global_load_ushort v95, v[96:97], off offset:1536
	s_waitcnt lgkmcnt(0)
	s_barrier
	ds_read_b32 v98, v82
	v_and_b32_e32 v30, 0xffff0000, v30
	v_lshlrev_b32_e32 v102, 16, v31
	v_and_b32_e32 v31, 0xffff0000, v31
	v_mov_b32_e32 v96, s20
	s_waitcnt lgkmcnt(0)
	v_mul_f32_e32 v28, v98, v28
	v_cvt_pk_bf16_f32 v28, v28, s0
	ds_write_b16 v91, v28 offset:53392
	v_mul_f32_e32 v28, v98, v100
	v_cvt_pk_bf16_f32 v28, v28, s0
	ds_write_b16 v91, v28 offset:53536
	v_mul_f32_e32 v28, v98, v29
	v_cvt_pk_bf16_f32 v28, v28, s0
	ds_write_b16 v91, v28 offset:53680
	v_mul_f32_e32 v28, v98, v101
	v_cvt_pk_bf16_f32 v28, v28, s0
	ds_write_b16 v91, v28 offset:53824
	v_mul_f32_e32 v28, v98, v30
	v_cvt_pk_bf16_f32 v28, v28, s0
	ds_write_b16 v91, v28 offset:53968
	v_mul_f32_e32 v28, v98, v102
	v_cvt_pk_bf16_f32 v28, v28, s0
	ds_write_b16 v91, v28 offset:54112
	v_mul_f32_e32 v28, v98, v31
	v_cvt_pk_bf16_f32 v28, v28, s0
	ds_write_b16 v91, v28 offset:54256
	ds_read_b32 v28, v83
	v_lshlrev_b32_e32 v29, 16, v24
	v_and_b32_e32 v24, 0xffff0000, v24
	v_mul_f32_e32 v99, v98, v99
	v_cvt_pk_bf16_f32 v99, v99, s0
	s_waitcnt lgkmcnt(0)
	v_mul_f32_e32 v24, v28, v24
	v_lshlrev_b32_e32 v30, 16, v25
	v_cvt_pk_bf16_f32 v24, v24, s0
	ds_write_b16 v91, v99 offset:53248
	ds_write_b16 v92, v24 offset:53392
	v_mul_f32_e32 v24, v28, v30
	v_and_b32_e32 v25, 0xffff0000, v25
	v_cvt_pk_bf16_f32 v24, v24, s0
	ds_write_b16 v92, v24 offset:53536
	v_mul_f32_e32 v24, v28, v25
	v_lshlrev_b32_e32 v31, 16, v26
	v_cvt_pk_bf16_f32 v24, v24, s0
	ds_write_b16 v92, v24 offset:53680
	v_mul_f32_e32 v24, v28, v31
	v_and_b32_e32 v26, 0xffff0000, v26
	v_cvt_pk_bf16_f32 v24, v24, s0
	ds_write_b16 v92, v24 offset:53824
	v_mul_f32_e32 v24, v28, v26
	v_lshlrev_b32_e32 v98, 16, v27
	v_cvt_pk_bf16_f32 v24, v24, s0
	ds_write_b16 v92, v24 offset:53968
	v_mul_f32_e32 v24, v28, v98
	v_and_b32_e32 v27, 0xffff0000, v27
	v_cvt_pk_bf16_f32 v24, v24, s0
	ds_write_b16 v92, v24 offset:54112
	v_mul_f32_e32 v24, v28, v27
	v_cvt_pk_bf16_f32 v24, v24, s0
	ds_read_b32 v97, v96
	ds_write_b16 v92, v24 offset:54256
	ds_read_b32 v24, v81
	v_mul_f32_e32 v29, v28, v29
	v_cvt_pk_bf16_f32 v29, v29, s0
	ds_write_b16 v92, v29 offset:53248
	s_waitcnt lgkmcnt(3)
	v_add_f32_e32 v86, v86, v97
	s_waitcnt lgkmcnt(1)
	v_sub_f32_e32 v24, v97, v24
	v_mul_f32_e32 v24, 0x3fb8aa3b, v24
	v_exp_f32_e32 v26, v24
	ds_read_b64 v[24:25], v93 offset:17408
	s_add_i32 s7, s7, 1
	s_cmp_lg_u32 s7, 10
	s_waitcnt lgkmcnt(0)
	v_lshlrev_b32_e32 v27, 16, v24
	v_and_b32_e32 v24, 0xffff0000, v24
	v_mul_f32_e32 v27, v26, v27
	v_mul_f32_e32 v24, v26, v24
	v_cvt_pk_bf16_f32 v27, v27, s0
	v_cvt_pk_bf16_f32 v24, v24, s0
	ds_write_b16 v84, v27 offset:34816
	ds_write_b16 v85, v24 offset:34960
	v_lshlrev_b32_e32 v24, 16, v25
	v_mul_f32_e32 v24, v26, v24
	v_cvt_pk_bf16_f32 v24, v24, s0
	ds_write_b16 v85, v24 offset:35104
	v_and_b32_e32 v24, 0xffff0000, v25
	v_mul_f32_e32 v24, v26, v24
	v_cvt_pk_bf16_f32 v24, v24, s0
	ds_write_b16 v85, v24 offset:35248
	ds_read_b64 v[24:25], v93 offset:17416
	s_waitcnt lgkmcnt(0)
	v_lshlrev_b32_e32 v27, 16, v24
	v_and_b32_e32 v24, 0xffff0000, v24
	v_mul_f32_e32 v27, v26, v27
	v_mul_f32_e32 v24, v26, v24
	v_cvt_pk_bf16_f32 v27, v27, s0
	v_cvt_pk_bf16_f32 v24, v24, s0
	ds_write_b16 v84, v27 offset:35392
	ds_write_b16 v85, v24 offset:35536
	v_lshlrev_b32_e32 v24, 16, v25
	v_mul_f32_e32 v24, v26, v24
	v_cvt_pk_bf16_f32 v24, v24, s0
	ds_write_b16 v85, v24 offset:35680
	v_and_b32_e32 v24, 0xffff0000, v25
	v_mul_f32_e32 v24, v26, v24
	v_cvt_pk_bf16_f32 v24, v24, s0
	ds_write_b16 v85, v24 offset:35824
	ds_read_b64 v[24:25], v93 offset:17424
	s_waitcnt lgkmcnt(0)
	v_lshlrev_b32_e32 v27, 16, v24
	v_and_b32_e32 v24, 0xffff0000, v24
	v_mul_f32_e32 v27, v26, v27
	v_mul_f32_e32 v24, v26, v24
	v_cvt_pk_bf16_f32 v27, v27, s0
	v_cvt_pk_bf16_f32 v24, v24, s0
	ds_write_b16 v84, v27 offset:35968
	ds_write_b16 v85, v24 offset:36112
	v_lshlrev_b32_e32 v24, 16, v25
	v_mul_f32_e32 v24, v26, v24
	v_cvt_pk_bf16_f32 v24, v24, s0
	ds_write_b16 v85, v24 offset:36256
	v_and_b32_e32 v24, 0xffff0000, v25
	v_mul_f32_e32 v24, v26, v24
	v_cvt_pk_bf16_f32 v24, v24, s0
	ds_write_b16 v85, v24 offset:36400
	ds_read_b64 v[24:25], v93 offset:17432
	s_waitcnt lgkmcnt(0)
; DI f32x4 mfma16(bf16x8 a, bf16x8 b, f32x4 c) { return __builtin_amdgcn_mfma_f32_16x16x32_bf16(a, b, c, 0, 0, 0); }
; template <int PROBE, int SONLY, int CPS>
; DI void ssd_chunk_loop(const Params& p, int layer, int b, int e, int c0, f32x4 (&h)[8], float& dtot, bool write_final) {
;     ...
;     if (!(PROBE & 8)) {
;       const float cd = __expf(acs_s[63]);
; #pragma unroll
;       for (int nt = 0; nt < 8; ++nt) h[nt] *= cd;
; #pragma unroll
;       for (int ks = 0; ks < 2; ++ks) {
;         const bf16x8 xf = ldfrag(Xt, 72, w * 16, ks * 32, lane);
; #pragma unroll
;         for (int nt = 0; nt < 8; ++nt) h[nt] = mfma16(ldfrag(Bt2, 72, nt * 16, ks * 32, lane), xf, h[nt]);
;       }
;     }
	v_lshlrev_b32_e32 v27, 16, v24
	v_and_b32_e32 v24, 0xffff0000, v24
	v_mul_f32_e32 v27, v26, v27
	v_mul_f32_e32 v24, v26, v24
	v_cvt_pk_bf16_f32 v27, v27, s0
	v_cvt_pk_bf16_f32 v24, v24, s0
	ds_write_b16 v84, v27 offset:36544
	ds_write_b16 v85, v24 offset:36688
	v_lshlrev_b32_e32 v24, 16, v25
	v_mul_f32_e32 v24, v26, v24
	v_cvt_pk_bf16_f32 v24, v24, s0
	ds_write_b16 v85, v24 offset:36832
	v_and_b32_e32 v24, 0xffff0000, v25
	v_mul_f32_e32 v24, v26, v24
	v_cvt_pk_bf16_f32 v24, v24, s0
	ds_write_b16 v85, v24 offset:36976
	ds_read_b64 v[24:25], v93 offset:17440
	s_waitcnt lgkmcnt(0)
	v_lshlrev_b32_e32 v27, 16, v24
	v_and_b32_e32 v24, 0xffff0000, v24
	v_mul_f32_e32 v27, v26, v27
	v_mul_f32_e32 v24, v26, v24
	v_cvt_pk_bf16_f32 v27, v27, s0
	v_cvt_pk_bf16_f32 v24, v24, s0
	ds_write_b16 v84, v27 offset:37120
	ds_write_b16 v85, v24 offset:37264
	v_lshlrev_b32_e32 v24, 16, v25
	v_mul_f32_e32 v24, v26, v24
	v_cvt_pk_bf16_f32 v24, v24, s0
	ds_write_b16 v85, v24 offset:37408
	v_and_b32_e32 v24, 0xffff0000, v25
	v_mul_f32_e32 v24, v26, v24
	v_cvt_pk_bf16_f32 v24, v24, s0
	ds_write_b16 v85, v24 offset:37552
	ds_read_b64 v[24:25], v93 offset:17448
	s_waitcnt lgkmcnt(0)
	v_lshlrev_b32_e32 v27, 16, v24
	v_and_b32_e32 v24, 0xffff0000, v24
	v_mul_f32_e32 v27, v26, v27
	v_mul_f32_e32 v24, v26, v24
	v_cvt_pk_bf16_f32 v27, v27, s0
	v_cvt_pk_bf16_f32 v24, v24, s0
	ds_write_b16 v84, v27 offset:37696
	ds_write_b16 v85, v24 offset:37840
	v_lshlrev_b32_e32 v24, 16, v25
	v_mul_f32_e32 v24, v26, v24
	v_cvt_pk_bf16_f32 v24, v24, s0
	ds_write_b16 v85, v24 offset:37984
	v_and_b32_e32 v24, 0xffff0000, v25
	v_mul_f32_e32 v24, v26, v24
	v_cvt_pk_bf16_f32 v24, v24, s0
	ds_write_b16 v85, v24 offset:38128
	ds_read_b64 v[24:25], v93 offset:17456
	s_waitcnt lgkmcnt(0)
	v_lshlrev_b32_e32 v27, 16, v24
	v_and_b32_e32 v24, 0xffff0000, v24
	v_mul_f32_e32 v27, v26, v27
	v_mul_f32_e32 v24, v26, v24
	v_cvt_pk_bf16_f32 v27, v27, s0
	v_cvt_pk_bf16_f32 v24, v24, s0
	ds_write_b16 v84, v27 offset:38272
	ds_write_b16 v85, v24 offset:38416
	v_lshlrev_b32_e32 v24, 16, v25
	v_mul_f32_e32 v24, v26, v24
	v_cvt_pk_bf16_f32 v24, v24, s0
	ds_write_b16 v85, v24 offset:38560
	v_and_b32_e32 v24, 0xffff0000, v25
	v_mul_f32_e32 v24, v26, v24
	v_cvt_pk_bf16_f32 v24, v24, s0
	ds_write_b16 v85, v24 offset:38704
	ds_read_b64 v[24:25], v93 offset:17464
	s_waitcnt lgkmcnt(0)
	v_lshlrev_b32_e32 v27, 16, v24
	v_and_b32_e32 v24, 0xffff0000, v24
	v_mul_f32_e32 v27, v26, v27
	v_mul_f32_e32 v24, v26, v24
	v_cvt_pk_bf16_f32 v27, v27, s0
	v_cvt_pk_bf16_f32 v24, v24, s0
	ds_write_b16 v84, v27 offset:38848
	ds_write_b16 v85, v24 offset:38992
	v_lshlrev_b32_e32 v24, 16, v25
	v_mul_f32_e32 v24, v26, v24
	v_cvt_pk_bf16_f32 v24, v24, s0
	ds_write_b16 v85, v24 offset:39136
	v_and_b32_e32 v24, 0xffff0000, v25
	v_mul_f32_e32 v24, v26, v24
	v_cvt_pk_bf16_f32 v24, v24, s0
	ds_write_b16 v85, v24 offset:39280
	s_waitcnt lgkmcnt(0)
	s_barrier
	ds_read_b32 v24, v96
	ds_read_b128 v[224:227], v68 offset:53248
	ds_read_b128 v[228:231], v94 offset:34816
	ds_read_b128 v[232:235], v94 offset:37120
	ds_read_b128 v[236:239], v94 offset:39424
	ds_read_b128 v[240:243], v94 offset:41728
	ds_read_b128 v[244:247], v94 offset:44032
	ds_read_b128 v[248:251], v94 offset:46336
	s_waitcnt lgkmcnt(7)
	v_mul_f32_e32 v24, 0x3fb8aa3b, v24
	v_exp_f32_e32 v96, v24
	s_nop 0
	v_pk_mul_f32 v[26:27], v[62:63], v[96:97] op_sel_hi:[1,0]
	v_pk_mul_f32 v[24:25], v[60:61], v[96:97] op_sel_hi:[1,0]
	v_pk_mul_f32 v[30:31], v[58:59], v[96:97] op_sel_hi:[1,0]
	v_pk_mul_f32 v[28:29], v[56:57], v[96:97] op_sel_hi:[1,0]
	s_waitcnt lgkmcnt(5)
	v_mfma_f32_16x16x32_bf16 v[24:27], v[228:231], v[224:227], v[24:27]
	ds_read_b128 v[228:231], v94 offset:48640
	v_pk_mul_f32 v[54:55], v[54:55], v[96:97] op_sel_hi:[1,0]
	v_pk_mul_f32 v[52:53], v[52:53], v[96:97] op_sel_hi:[1,0]
	s_waitcnt lgkmcnt(5)
	v_mfma_f32_16x16x32_bf16 v[28:31], v[232:235], v[224:227], v[28:31]
	ds_read_b128 v[232:235], v94 offset:50944
	v_pk_mul_f32 v[50:51], v[50:51], v[96:97] op_sel_hi:[1,0]
	v_pk_mul_f32 v[48:49], v[48:49], v[96:97] op_sel_hi:[1,0]
	s_waitcnt lgkmcnt(5)
	v_mfma_f32_16x16x32_bf16 v[52:55], v[236:239], v[224:227], v[52:55]
	ds_read_b128 v[236:239], v94 offset:34880
	v_pk_mul_f32 v[46:47], v[46:47], v[96:97] op_sel_hi:[1,0]
	v_pk_mul_f32 v[44:45], v[44:45], v[96:97] op_sel_hi:[1,0]
	s_waitcnt lgkmcnt(5)
	v_mfma_f32_16x16x32_bf16 v[48:51], v[240:243], v[224:227], v[48:51]
	ds_read_b128 v[240:243], v94 offset:37184
	v_pk_mul_f32 v[38:39], v[38:39], v[96:97] op_sel_hi:[1,0]
	v_pk_mul_f32 v[36:37], v[36:37], v[96:97] op_sel_hi:[1,0]
	s_waitcnt lgkmcnt(5)
	v_mfma_f32_16x16x32_bf16 v[44:47], v[244:247], v[224:227], v[44:47]
	ds_read_b128 v[244:247], v94 offset:39488
	v_pk_mul_f32 v[42:43], v[42:43], v[96:97] op_sel_hi:[1,0]
	v_pk_mul_f32 v[40:41], v[40:41], v[96:97] op_sel_hi:[1,0]
	s_waitcnt lgkmcnt(5)
	v_mfma_f32_16x16x32_bf16 v[36:39], v[248:251], v[224:227], v[36:39]
	ds_read_b128 v[248:251], v94 offset:41792
	v_pk_mul_f32 v[34:35], v[34:35], v[96:97] op_sel_hi:[1,0]
	v_pk_mul_f32 v[32:33], v[32:33], v[96:97] op_sel_hi:[1,0]
	s_waitcnt lgkmcnt(5)
	v_mfma_f32_16x16x32_bf16 v[40:43], v[228:231], v[224:227], v[40:43]
	ds_read_b128 v[228:231], v94 offset:44096
	s_waitcnt lgkmcnt(5)
	v_mfma_f32_16x16x32_bf16 v[32:35], v[232:235], v[224:227], v[32:35]
	ds_read_b128 v[224:227], v94 offset:46400
	ds_read_b128 v[232:235], v94 offset:48704
	ds_read_b128 v[96:99], v68 offset:53312
	s_waitcnt lgkmcnt(0)
	v_mfma_f32_16x16x32_bf16 v[60:63], v[236:239], v[96:99], v[24:27]
	s_nop 2
	v_mfma_f32_16x16x32_bf16 v[56:59], v[240:243], v[96:99], v[28:31]
	v_mfma_f32_16x16x32_bf16 v[52:55], v[244:247], v[96:99], v[52:55]
	v_mfma_f32_16x16x32_bf16 v[48:51], v[248:251], v[96:99], v[48:51]
	v_mfma_f32_16x16x32_bf16 v[44:47], v[228:231], v[96:99], v[44:47]
	v_mfma_f32_16x16x32_bf16 v[36:39], v[224:227], v[96:99], v[36:39]
	v_mfma_f32_16x16x32_bf16 v[40:43], v[232:235], v[96:99], v[40:43]
	ds_read_b128 v[24:27], v94 offset:51008
	s_waitcnt lgkmcnt(0)
	s_waitcnt lgkmcnt(0)
	s_barrier
	v_mfma_f32_16x16x32_bf16 v[32:35], v[24:27], v[96:99], v[32:35]
	s_cbranch_scc0 .LBB0_486
	s_waitcnt vmcnt(2)
	v_mov_b32_e32 v28, v16
	v_mov_b32_e32 v29, v17
	v_mov_b32_e32 v30, v18
	v_mov_b32_e32 v31, v19
	s_waitcnt vmcnt(1)
	v_mov_b32_e32 v24, v20
	v_mov_b32_e32 v25, v21
	v_mov_b32_e32 v26, v22
	v_mov_b32_e32 v27, v23
	s_branch .LBB0_479

; DI f32x4 mfma16(bf16x8 a, bf16x8 b, f32x4 c) { return __builtin_amdgcn_mfma_f32_16x16x32_bf16(a, b, c, 0, 0, 0); }
; template <int PROBE, int SONLY, int CPS>
; DI void ssd_chunk_loop(const Params& p, int layer, int b, int e, int c0, f32x4 (&h)[8], float& dtot, bool write_final) {
;     ...
;         *(uint2*)(Ms + q * 72 + s0) = ov;
;       }
;     }
;     f32x4 y[4];
; #pragma unroll
;     for (int qt = 0; qt < 4; ++qt) y[qt] = (f32x4){0.f, 0.f, 0.f, 0.f};
;     if (!(PROBE & 4) && !SONLY)
; #pragma unroll
;     for (int kk = 0; kk < 4; ++kk) {
;       const bf16x8 hf = packfrag(h[2 * kk], h[2 * kk + 1]);
; #pragma unroll
;       for (int qt = 0; qt < 4; ++qt) y[qt] = mfma16(hf, ldfrag_perm(Cs, 136, qt * 16, kk * 32, lane), y[qt]);
;     }
.LBB0_543:
	s_or_b64 exec, exec, s[6:7]
	v_cvt_pk_bf16_f32 v106, v120, v108
	v_cvt_pk_bf16_f32 v107, v104, v105
	ds_write_b64 v227, v[106:107] offset:62560
	ds_read2_b64 v[0:3], v245 offset1:4
	v_add_u32_e32 v149, 0x1000, v245
	ds_read2_b64 v[4:7], v149 offset0:32 offset1:36
	v_add_u32_e32 v155, 0x2000, v245
	ds_read2_b64 v[8:11], v155 offset0:64 offset1:68
	v_add_u32_e32 v165, 0x3000, v245
	ds_read2_b64 v[12:15], v165 offset0:96 offset1:100
	ds_read2_b64 v[16:19], v245 offset0:8 offset1:12
	ds_read2_b64 v[20:23], v149 offset0:40 offset1:44
	ds_read2_b64 v[24:27], v155 offset0:72 offset1:76
	ds_read2_b64 v[28:31], v165 offset0:104 offset1:108
	v_cvt_pk_bf16_f32 v104, v64, v65
	v_cvt_pk_bf16_f32 v105, v66, v67
	v_cvt_pk_bf16_f32 v106, v68, v69
	v_cvt_pk_bf16_f32 v107, v70, v71
	s_waitcnt lgkmcnt(7)
	s_nop 0
	v_mfma_f32_16x16x32_bf16 v[108:111], v[104:107], v[0:3], 0
	ds_read2_b64 v[0:3], v245 offset0:16 offset1:20
	s_waitcnt lgkmcnt(7)
	v_mfma_f32_16x16x32_bf16 v[112:115], v[104:107], v[4:7], 0
	ds_read2_b64 v[4:7], v149 offset0:48 offset1:52
	s_waitcnt lgkmcnt(7)
	v_mfma_f32_16x16x32_bf16 v[116:119], v[104:107], v[8:11], 0
	ds_read2_b64 v[8:11], v155 offset0:80 offset1:84
	s_waitcnt lgkmcnt(7)
	v_mfma_f32_16x16x32_bf16 v[104:107], v[104:107], v[12:15], 0
	ds_read2_b64 v[12:15], v165 offset0:112 offset1:116
	v_cvt_pk_bf16_f32 v120, v72, v73
	v_cvt_pk_bf16_f32 v121, v74, v75
	v_cvt_pk_bf16_f32 v122, v76, v77
	v_cvt_pk_bf16_f32 v123, v78, v79
	s_nop 0
	s_waitcnt lgkmcnt(7)
	v_mfma_f32_16x16x32_bf16 v[108:111], v[120:123], v[16:19], v[108:111]
	ds_read2_b64 v[16:19], v245 offset0:24 offset1:28
	s_waitcnt lgkmcnt(7)
	v_mfma_f32_16x16x32_bf16 v[112:115], v[120:123], v[20:23], v[112:115]
	ds_read2_b64 v[20:23], v149 offset0:56 offset1:60
	s_waitcnt lgkmcnt(7)
	v_mfma_f32_16x16x32_bf16 v[116:119], v[120:123], v[24:27], v[116:119]
	ds_read2_b64 v[24:27], v155 offset0:88 offset1:92
	s_waitcnt lgkmcnt(7)
	v_mfma_f32_16x16x32_bf16 v[104:107], v[120:123], v[28:31], v[104:107]
	v_cvt_pk_bf16_f32 v120, v80, v81
	v_cvt_pk_bf16_f32 v121, v82, v83
	v_cvt_pk_bf16_f32 v122, v84, v85
	v_cvt_pk_bf16_f32 v123, v86, v87
	s_waitcnt lgkmcnt(6)
	s_nop 0
	v_mfma_f32_16x16x32_bf16 v[108:111], v[120:123], v[0:3], v[108:111]
	s_waitcnt lgkmcnt(5)
	v_mfma_f32_16x16x32_bf16 v[112:115], v[120:123], v[4:7], v[112:115]
	s_waitcnt lgkmcnt(4)
	v_mfma_f32_16x16x32_bf16 v[116:119], v[120:123], v[8:11], v[116:119]
	s_waitcnt lgkmcnt(3)
	v_mfma_f32_16x16x32_bf16 v[104:107], v[120:123], v[12:15], v[104:107]
	v_cvt_pk_bf16_f32 v120, v88, v89
	v_cvt_pk_bf16_f32 v121, v90, v91
	v_cvt_pk_bf16_f32 v122, v92, v93
	v_cvt_pk_bf16_f32 v123, v94, v95
	s_waitcnt lgkmcnt(2)
	s_nop 0
	v_mfma_f32_16x16x32_bf16 v[108:111], v[120:123], v[16:19], v[108:111]
	v_mov_b32_e32 v149, s20
	s_waitcnt lgkmcnt(1)
	v_mfma_f32_16x16x32_bf16 v[112:115], v[120:123], v[20:23], v[112:115]
	s_waitcnt lgkmcnt(0)
	v_mfma_f32_16x16x32_bf16 v[116:119], v[120:123], v[24:27], v[116:119]
	ds_read2_b64 v[124:127], v165 offset0:120 offset1:124
	s_waitcnt lgkmcnt(0)
	v_mfma_f32_16x16x32_bf16 v[104:107], v[120:123], v[124:127], v[104:107]
	ds_read2_b32 v[120:121], v211 offset1:16
	ds_read2_b32 v[122:123], v211 offset0:32 offset1:48
	s_waitcnt lgkmcnt(0)
	s_waitcnt lgkmcnt(0)
	s_barrier
; DI unsigned pack2(float a, float b) { fl2_t v = {a, b}; return __builtin_bit_cast(unsigned, __builtin_convertvector(v, bf2_t)); }
; DI float bflo(unsigned u) { return __uint_as_float(u << 16); }
; DI float bfhi(unsigned u) { return __uint_as_float(u & 0xffff0000u); }
; DI f32x4 mfma16(bf16x8 a, bf16x8 b, f32x4 c) { return __builtin_amdgcn_mfma_f32_16x16x32_bf16(a, b, c, 0, 0, 0); }
; DI float silu_f(float x) { return x * __builtin_amdgcn_rcpf(1.f + __expf(-x)); }
; template <int PROBE, int SONLY, int CPS>
; DI void ssd_chunk_loop(const Params& p, int layer, int b, int e, int c0, f32x4 (&h)[8], float& dtot, bool write_final) {
;     ...
;     if (!SONLY) {
; #pragma unroll
;     for (int qt = 0; qt < 4; ++qt) y[qt] *= __expf(acs_s[qt * 16 + l15]);
;     __syncthreads();
;     }
;     if (!(PROBE & 8) && !SONLY)
; #pragma unroll
;     for (int qt = 0; qt < 4; ++qt)
; #pragma unroll
;       for (int ks = 0; ks < 2; ++ks)
;         if (ks == 0 || qt >= 2) y[qt] = mfma16(ldfrag(Xt, 72, w * 16, ks * 32, lane), ldfrag(Ms, 72, qt * 16, ks * 32, lane), y[qt]);
;     if (!(PROBE & 8)) {
;       const float cd = __expf(acs_s[63]);
; #pragma unroll
;       for (int nt = 0; nt < 8; ++nt) h[nt] *= cd;
; #pragma unroll
;       for (int ks = 0; ks < 2; ++ks) {
;         const bf16x8 xf = ldfrag(Xt, 72, w * 16, ks * 32, lane);
; #pragma unroll
;         for (int nt = 0; nt < 8; ++nt) h[nt] = mfma16(ldfrag(Bt2, 72, nt * 16, ks * 32, lane), xf, h[nt]);
;       }
;     }
;     if (!SONLY)
; #pragma unroll
;     for (int qt = 0; qt < 4; ++qt) {
;       const int q = qt * 16 + l15;
;       const size_t row = (size_t)(base + q);
;       const int pcol = w * 16 + quad * 4;
;       const uint2 xv = dx[qt];
;       const uint2 zv = dz[qt];
;       const float y0 = (y[qt][0] + Dv * bflo(xv.x)) * silu_f(bflo(zv.x));
;       const float y1 = (y[qt][1] + Dv * bfhi(xv.x)) * silu_f(bfhi(zv.x));
;       const float y2 = (y[qt][2] + Dv * bflo(xv.y)) * silu_f(bflo(zv.y));
;       const float y3 = (y[qt][3] + Dv * bfhi(xv.y)) * silu_f(bfhi(zv.y));
;       uint2 ov; ov.x = pack2(y0, y1); ov.y = pack2(y2, y3);
;       if (do_store) *(uint2*)(MIX + row * 2048 + 1280 + e * 64 + pcol) = ov;
;       float ss = y0 * y0 + y1 * y1 + y2 * y2 + y3 * y3;
;       ss += __shfl_xor(ss, 16);
;       ss += __shfl_xor(ss, 32);
;       if (quad == 0) ssq_s[w * 64 + q] = ss;
	ds_read_b128 v[0:3], v212 offset:53248
	ds_read_b128 v[4:7], v246 offset:62464
	ds_read_b128 v[8:11], v246 offset:64768
	ds_read_b128 v[12:15], v247 offset:62464
	ds_read_b128 v[16:19], v247 offset:62528
	ds_read_b32 v20, v149
	ds_read_b128 v[24:27], v247 offset:64768
	ds_read_b128 v[28:31], v246 offset:34816
	v_mul_f32_e32 v120, 0x3fb8aa3b, v120
	v_exp_f32_e32 v120, v120
	v_mul_f32_e32 v123, 0x3fb8aa3b, v123
	v_exp_f32_e32 v124, v123
	v_pk_mul_f32 v[110:111], v[110:111], v[120:121] op_sel_hi:[1,0]
	v_pk_mul_f32 v[108:109], v[108:109], v[120:121] op_sel_hi:[1,0]
	v_mul_f32_e32 v120, 0x3fb8aa3b, v121
	v_exp_f32_e32 v120, v120
	v_pk_mul_f32 v[106:107], v[106:107], v[124:125] op_sel_hi:[1,0]
	v_pk_mul_f32 v[104:105], v[104:105], v[124:125] op_sel_hi:[1,0]
	v_pk_mul_f32 v[114:115], v[114:115], v[120:121] op_sel_hi:[1,0]
	v_pk_mul_f32 v[112:113], v[112:113], v[120:121] op_sel_hi:[1,0]
	v_mul_f32_e32 v120, 0x3fb8aa3b, v122
	v_exp_f32_e32 v120, v120
	s_nop 0
	v_pk_mul_f32 v[122:123], v[118:119], v[120:121] op_sel_hi:[1,0]
	v_pk_mul_f32 v[120:121], v[116:117], v[120:121] op_sel_hi:[1,0]
	s_waitcnt lgkmcnt(6)
	v_mfma_f32_16x16x32_bf16 v[116:119], v[0:3], v[4:7], v[108:111]
	ds_read_b128 v[4:7], v246 offset:37120
	s_nop 2
	s_waitcnt lgkmcnt(6)
	v_mfma_f32_16x16x32_bf16 v[112:115], v[0:3], v[8:11], v[112:115]
	ds_read_b128 v[8:11], v246 offset:39424
	s_waitcnt lgkmcnt(6)
	v_mfma_f32_16x16x32_bf16 v[108:111], v[0:3], v[12:15], v[120:123]
	ds_read_b128 v[12:15], v246 offset:41728
	s_nop 2
	ds_read_b128 v[120:123], v212 offset:53312
	s_waitcnt lgkmcnt(6)
	v_mul_f32_e32 v149, 0x3fb8aa3b, v20
	ds_read_b128 v[20:23], v246 offset:44032
	s_waitcnt lgkmcnt(1)
	v_mfma_f32_16x16x32_bf16 v[108:111], v[120:123], v[16:19], v[108:111]
	ds_read_b128 v[16:19], v246 offset:46336
	v_mfma_f32_16x16x32_bf16 v[104:107], v[0:3], v[24:27], v[104:107]
	ds_read_b128 v[24:27], v246 offset:48640
	ds_read_b128 v[248:251], v247 offset:64832
	s_waitcnt lgkmcnt(0)
	v_mfma_f32_16x16x32_bf16 v[104:107], v[120:123], v[248:251], v[104:107]
	v_exp_f32_e32 v248, v149
	s_nop 0
	v_pk_mul_f32 v[66:67], v[66:67], v[248:249] op_sel_hi:[1,0]
	v_pk_mul_f32 v[64:65], v[64:65], v[248:249] op_sel_hi:[1,0]
	v_pk_mul_f32 v[70:71], v[70:71], v[248:249] op_sel_hi:[1,0]
	v_pk_mul_f32 v[68:69], v[68:69], v[248:249] op_sel_hi:[1,0]
	v_pk_mul_f32 v[74:75], v[74:75], v[248:249] op_sel_hi:[1,0]
	v_pk_mul_f32 v[72:73], v[72:73], v[248:249] op_sel_hi:[1,0]
	v_pk_mul_f32 v[78:79], v[78:79], v[248:249] op_sel_hi:[1,0]
	v_pk_mul_f32 v[76:77], v[76:77], v[248:249] op_sel_hi:[1,0]
	v_pk_mul_f32 v[82:83], v[82:83], v[248:249] op_sel_hi:[1,0]
	v_pk_mul_f32 v[80:81], v[80:81], v[248:249] op_sel_hi:[1,0]
	v_pk_mul_f32 v[86:87], v[86:87], v[248:249] op_sel_hi:[1,0]
	v_pk_mul_f32 v[84:85], v[84:85], v[248:249] op_sel_hi:[1,0]
	v_pk_mul_f32 v[90:91], v[90:91], v[248:249] op_sel_hi:[1,0]
	v_pk_mul_f32 v[88:89], v[88:89], v[248:249] op_sel_hi:[1,0]
	v_pk_mul_f32 v[94:95], v[94:95], v[248:249] op_sel_hi:[1,0]
	v_pk_mul_f32 v[92:93], v[92:93], v[248:249] op_sel_hi:[1,0]
	v_mfma_f32_16x16x32_bf16 v[64:67], v[28:31], v[0:3], v[64:67]
	ds_read_b128 v[28:31], v246 offset:34880
	v_mfma_f32_16x16x32_bf16 v[68:71], v[4:7], v[0:3], v[68:71]
	ds_read_b128 v[4:7], v246 offset:37184
	v_mfma_f32_16x16x32_bf16 v[72:75], v[8:11], v[0:3], v[72:75]
	ds_read_b128 v[8:11], v246 offset:39488
	v_mfma_f32_16x16x32_bf16 v[76:79], v[12:15], v[0:3], v[76:79]
	ds_read_b128 v[12:15], v246 offset:41792
	v_mfma_f32_16x16x32_bf16 v[80:83], v[20:23], v[0:3], v[80:83]
	ds_read_b128 v[20:23], v246 offset:44096
	v_mfma_f32_16x16x32_bf16 v[84:87], v[16:19], v[0:3], v[84:87]
	ds_read_b128 v[16:19], v246 offset:46400
	v_mfma_f32_16x16x32_bf16 v[88:91], v[24:27], v[0:3], v[88:91]
	ds_read_b128 v[24:27], v246 offset:48704
	ds_read_b128 v[248:251], v246 offset:50944
	s_waitcnt lgkmcnt(0)
	v_mfma_f32_16x16x32_bf16 v[92:95], v[248:251], v[0:3], v[92:95]
	v_mfma_f32_16x16x32_bf16 v[64:67], v[28:31], v[120:123], v[64:67]
	v_mfma_f32_16x16x32_bf16 v[68:71], v[4:7], v[120:123], v[68:71]
	v_mfma_f32_16x16x32_bf16 v[72:75], v[8:11], v[120:123], v[72:75]
	v_mfma_f32_16x16x32_bf16 v[76:79], v[12:15], v[120:123], v[76:79]
	v_mfma_f32_16x16x32_bf16 v[80:83], v[20:23], v[120:123], v[80:83]
	v_mfma_f32_16x16x32_bf16 v[84:87], v[16:19], v[120:123], v[84:87]
	v_mfma_f32_16x16x32_bf16 v[88:91], v[24:27], v[120:123], v[88:91]
	ds_read_b128 v[124:127], v246 offset:51008
	s_waitcnt lgkmcnt(0)
	v_mfma_f32_16x16x32_bf16 v[92:95], v[124:127], v[120:123], v[92:95]
	s_waitcnt vmcnt(7)
	v_lshlrev_b32_e32 v120, 16, v172
	s_waitcnt vmcnt(6)
	v_lshlrev_b32_e32 v122, 16, v170
	v_and_b32_e32 v121, 0xffff0000, v172
	v_and_b32_e32 v123, 0xffff0000, v170
	v_mul_f32_e32 v124, 0xbfb8aa3b, v122
	v_pk_fma_f32 v[116:117], v[128:129], v[120:121], v[116:117]
	v_mul_f32_e32 v120, 0xbfb8aa3b, v123
	v_exp_f32_e32 v124, v124
	v_exp_f32_e32 v120, v120
	v_add_f32_e32 v124, 1.0, v124
	v_add_f32_e32 v120, 1.0, v120
	v_rcp_f32_e32 v124, v124
	v_rcp_f32_e32 v125, v120
	s_nop 0
	v_pk_mul_f32 v[120:121], v[124:125], v[122:123]
	s_nop 0
	v_pk_mul_f32 v[116:117], v[120:121], v[116:117]
	v_lshlrev_b32_e32 v120, 16, v173
	v_lshlrev_b32_e32 v122, 16, v171
	v_and_b32_e32 v121, 0xffff0000, v173
	v_and_b32_e32 v123, 0xffff0000, v171
	v_mul_f32_e32 v124, 0xbfb8aa3b, v122
	v_pk_fma_f32 v[118:119], v[128:129], v[120:121], v[118:119]
	v_mul_f32_e32 v120, 0xbfb8aa3b, v123
	v_exp_f32_e32 v124, v124
	v_exp_f32_e32 v120, v120
	v_add_f32_e32 v124, 1.0, v124
	v_add_f32_e32 v120, 1.0, v120
	v_rcp_f32_e32 v124, v124
	v_rcp_f32_e32 v125, v120
	s_nop 0
	v_pk_mul_f32 v[120:121], v[124:125], v[122:123]
	s_nop 0
	v_pk_mul_f32 v[118:119], v[120:121], v[118:119]
	v_cvt_pk_bf16_f32 v120, v116, v117
	v_pk_mul_f32 v[116:117], v[116:117], v[116:117]
	v_cvt_pk_bf16_f32 v121, v118, v119
	v_pk_mul_f32 v[118:119], v[118:119], v[118:119]
	v_add_f32_e32 v116, v116, v117
	v_add_f32_e32 v116, v118, v116
	v_add_f32_e32 v116, v119, v116
	ds_bpermute_b32 v117, v213, v116
	v_lshlrev_b64 v[122:123], 12, v[160:161]
	v_lshl_add_u64 v[122:123], s[94:95], 0, v[122:123]
	v_lshl_add_u64 v[122:123], v[122:123], 0, s[2:3]
	v_lshl_add_u64 v[122:123], v[134:135], 1, v[122:123]
	s_waitcnt lgkmcnt(0)
	v_add_f32_e32 v116, v116, v117
	ds_bpermute_b32 v117, v214, v116
	v_add_co_u32_e32 v122, vcc, s14, v122
	s_nop 1
	v_addc_co_u32_e32 v123, vcc, 0, v123, vcc
	global_store_dwordx2 v[122:123], v[120:121], off offset:2560
	s_and_saveexec_b64 s[6:7], s[38:39]
	s_cbranch_execz .LBB0_545
	s_waitcnt lgkmcnt(0)
	v_add_f32_e32 v116, v116, v117
	ds_write_b32 v240, v116

; DI f32x4 mfma16(bf16x8 a, bf16x8 b, f32x4 c) { return __builtin_amdgcn_mfma_f32_16x16x32_bf16(a, b, c, 0, 0, 0); }
; template <int PROBE, int SONLY, int CPS>
; DI void ssd_chunk_loop(const Params& p, int layer, int b, int e, int c0, f32x4 (&h)[8], float& dtot, bool write_final) {
;     ...
;         *(uint2*)(Ms + q * 72 + s0) = ov;
;       }
;     }
;     f32x4 y[4];
; #pragma unroll
;     for (int qt = 0; qt < 4; ++qt) y[qt] = (f32x4){0.f, 0.f, 0.f, 0.f};
;     if (!(PROBE & 4) && !SONLY)
; #pragma unroll
;     for (int kk = 0; kk < 4; ++kk) {
;       const bf16x8 hf = packfrag(h[2 * kk], h[2 * kk + 1]);
; #pragma unroll
;       for (int qt = 0; qt < 4; ++qt) y[qt] = mfma16(hf, ldfrag_perm(Cs, 136, qt * 16, kk * 32, lane), y[qt]);
;     }
.LBB0_595:
	s_or_b64 exec, exec, s[6:7]
	v_cvt_pk_bf16_f32 v74, v88, v76
	v_cvt_pk_bf16_f32 v75, v72, v73
	ds_write_b64 v177, v[74:75] offset:62560
	ds_read2_b64 v[224:227], v215 offset1:4
	v_add_u32_e32 v119, 0x1000, v215
	ds_read2_b64 v[228:231], v119 offset0:32 offset1:36
	v_add_u32_e32 v125, 0x2000, v215
	ds_read2_b64 v[232:235], v125 offset0:64 offset1:68
	v_add_u32_e32 v131, 0x3000, v215
	ds_read2_b64 v[236:239], v131 offset0:96 offset1:100
	ds_read2_b64 v[240:243], v215 offset0:8 offset1:12
	ds_read2_b64 v[244:247], v119 offset0:40 offset1:44
	ds_read2_b64 v[248:251], v125 offset0:72 offset1:76
	v_cvt_pk_bf16_f32 v72, v0, v1
	v_cvt_pk_bf16_f32 v73, v2, v3
	v_cvt_pk_bf16_f32 v74, v4, v5
	v_cvt_pk_bf16_f32 v75, v6, v7
	s_waitcnt lgkmcnt(6)
	s_nop 0
	v_mfma_f32_16x16x32_bf16 v[76:79], v[72:75], v[224:227], 0
	ds_read2_b64 v[224:227], v131 offset0:104 offset1:108
	v_ashrrev_i32_e32 v137, 31, v136
	s_waitcnt lgkmcnt(6)
	v_mfma_f32_16x16x32_bf16 v[80:83], v[72:75], v[228:231], 0
	ds_read2_b64 v[228:231], v215 offset0:16 offset1:20
	s_waitcnt lgkmcnt(6)
	v_mfma_f32_16x16x32_bf16 v[84:87], v[72:75], v[232:235], 0
	ds_read2_b64 v[232:235], v119 offset0:48 offset1:52
	s_waitcnt lgkmcnt(6)
	v_mfma_f32_16x16x32_bf16 v[72:75], v[72:75], v[236:239], 0
	ds_read2_b64 v[236:239], v125 offset0:80 offset1:84
	v_cvt_pk_bf16_f32 v88, v8, v9
	v_cvt_pk_bf16_f32 v89, v10, v11
	v_cvt_pk_bf16_f32 v90, v12, v13
	v_cvt_pk_bf16_f32 v91, v14, v15
	s_nop 0
	s_waitcnt lgkmcnt(6)
	v_mfma_f32_16x16x32_bf16 v[76:79], v[88:91], v[240:243], v[76:79]
	ds_read2_b64 v[240:243], v131 offset0:112 offset1:116
	s_waitcnt lgkmcnt(6)
	v_mfma_f32_16x16x32_bf16 v[80:83], v[88:91], v[244:247], v[80:83]
	ds_read2_b64 v[244:247], v215 offset0:24 offset1:28
	s_waitcnt lgkmcnt(6)
	v_mfma_f32_16x16x32_bf16 v[84:87], v[88:91], v[248:251], v[84:87]
	ds_read2_b64 v[248:251], v119 offset0:56 offset1:60
	s_waitcnt lgkmcnt(6)
	v_mfma_f32_16x16x32_bf16 v[72:75], v[88:91], v[224:227], v[72:75]
	ds_read2_b64 v[224:227], v125 offset0:88 offset1:92
	v_cvt_pk_bf16_f32 v88, v16, v17
	v_cvt_pk_bf16_f32 v89, v18, v19
	v_cvt_pk_bf16_f32 v90, v20, v21
	v_cvt_pk_bf16_f32 v91, v22, v23
	s_waitcnt lgkmcnt(6)
	s_nop 0
	v_mfma_f32_16x16x32_bf16 v[76:79], v[88:91], v[228:231], v[76:79]
	s_waitcnt lgkmcnt(5)
	v_mfma_f32_16x16x32_bf16 v[80:83], v[88:91], v[232:235], v[80:83]
	s_waitcnt lgkmcnt(4)
	v_mfma_f32_16x16x32_bf16 v[84:87], v[88:91], v[236:239], v[84:87]
	s_waitcnt lgkmcnt(3)
	v_mfma_f32_16x16x32_bf16 v[72:75], v[88:91], v[240:243], v[72:75]
	v_cvt_pk_bf16_f32 v88, v24, v25
	v_cvt_pk_bf16_f32 v89, v26, v27
	v_cvt_pk_bf16_f32 v90, v28, v29
	v_cvt_pk_bf16_f32 v91, v30, v31
	s_waitcnt lgkmcnt(2)
	s_nop 0
	v_mfma_f32_16x16x32_bf16 v[76:79], v[88:91], v[244:247], v[76:79]
	v_mov_b32_e32 v119, s20
	s_waitcnt lgkmcnt(1)
	v_mfma_f32_16x16x32_bf16 v[80:83], v[88:91], v[248:251], v[80:83]
	s_waitcnt lgkmcnt(0)
	v_mfma_f32_16x16x32_bf16 v[84:87], v[88:91], v[224:227], v[84:87]
	ds_read2_b64 v[92:95], v131 offset0:120 offset1:124
	s_waitcnt lgkmcnt(0)
	v_mfma_f32_16x16x32_bf16 v[72:75], v[88:91], v[92:95], v[72:75]
	ds_read2_b32 v[88:89], v157 offset1:16
	ds_read2_b32 v[90:91], v157 offset0:32 offset1:48
	s_waitcnt lgkmcnt(0)
	s_waitcnt lgkmcnt(0)
	s_barrier
; DI unsigned pack2(float a, float b) { fl2_t v = {a, b}; return __builtin_bit_cast(unsigned, __builtin_convertvector(v, bf2_t)); }
; DI float bflo(unsigned u) { return __uint_as_float(u << 16); }
; DI float bfhi(unsigned u) { return __uint_as_float(u & 0xffff0000u); }
; DI f32x4 mfma16(bf16x8 a, bf16x8 b, f32x4 c) { return __builtin_amdgcn_mfma_f32_16x16x32_bf16(a, b, c, 0, 0, 0); }
; DI float silu_f(float x) { return x * __builtin_amdgcn_rcpf(1.f + __expf(-x)); }
; template <int PROBE, int SONLY, int CPS>
; DI void ssd_chunk_loop(const Params& p, int layer, int b, int e, int c0, f32x4 (&h)[8], float& dtot, bool write_final) {
;     ...
;     if (!SONLY) {
; #pragma unroll
;     for (int qt = 0; qt < 4; ++qt) y[qt] *= __expf(acs_s[qt * 16 + l15]);
;     __syncthreads();
;     }
;     if (!(PROBE & 8) && !SONLY)
; #pragma unroll
;     for (int qt = 0; qt < 4; ++qt)
; #pragma unroll
;       for (int ks = 0; ks < 2; ++ks)
;         if (ks == 0 || qt >= 2) y[qt] = mfma16(ldfrag(Xt, 72, w * 16, ks * 32, lane), ldfrag(Ms, 72, qt * 16, ks * 32, lane), y[qt]);
;     if (!(PROBE & 8)) {
;       const float cd = __expf(acs_s[63]);
; #pragma unroll
;       for (int nt = 0; nt < 8; ++nt) h[nt] *= cd;
; #pragma unroll
;       for (int ks = 0; ks < 2; ++ks) {
;         const bf16x8 xf = ldfrag(Xt, 72, w * 16, ks * 32, lane);
; #pragma unroll
;         for (int nt = 0; nt < 8; ++nt) h[nt] = mfma16(ldfrag(Bt2, 72, nt * 16, ks * 32, lane), xf, h[nt]);
;       }
;     }
;     if (!SONLY)
; #pragma unroll
;     for (int qt = 0; qt < 4; ++qt) {
;       const int q = qt * 16 + l15;
;       const size_t row = (size_t)(base + q);
;       const int pcol = w * 16 + quad * 4;
;       const uint2 xv = dx[qt];
;       const uint2 zv = dz[qt];
;       const float y0 = (y[qt][0] + Dv * bflo(xv.x)) * silu_f(bflo(zv.x));
;       const float y1 = (y[qt][1] + Dv * bfhi(xv.x)) * silu_f(bfhi(zv.x));
;       const float y2 = (y[qt][2] + Dv * bflo(xv.y)) * silu_f(bflo(zv.y));
;       const float y3 = (y[qt][3] + Dv * bfhi(xv.y)) * silu_f(bfhi(zv.y));
;       uint2 ov; ov.x = pack2(y0, y1); ov.y = pack2(y2, y3);
;       if (do_store) *(uint2*)(MIX + row * 2048 + 1280 + e * 64 + pcol) = ov;
;       float ss = y0 * y0 + y1 * y1 + y2 * y2 + y3 * y3;
;       ss += __shfl_xor(ss, 16);
;       ss += __shfl_xor(ss, 32);
;       if (quad == 0) ssq_s[w * 64 + q] = ss;
	ds_read_b128 v[224:227], v158 offset:53248
	ds_read_b128 v[228:231], v216 offset:62464
	ds_read_b128 v[232:235], v216 offset:64768
	ds_read_b128 v[236:239], v217 offset:62464
	ds_read_b128 v[240:243], v217 offset:62528
	ds_read_b32 v244, v119
	ds_read_b128 v[248:251], v217 offset:64768
	v_mul_f32_e32 v88, 0x3fb8aa3b, v88
	v_exp_f32_e32 v88, v88
	v_mul_f32_e32 v91, 0x3fb8aa3b, v91
	v_exp_f32_e32 v92, v91
	v_pk_mul_f32 v[78:79], v[78:79], v[88:89] op_sel_hi:[1,0]
	v_pk_mul_f32 v[76:77], v[76:77], v[88:89] op_sel_hi:[1,0]
	v_mul_f32_e32 v88, 0x3fb8aa3b, v89
	v_exp_f32_e32 v88, v88
	v_pk_mul_f32 v[74:75], v[74:75], v[92:93] op_sel_hi:[1,0]
	v_pk_mul_f32 v[72:73], v[72:73], v[92:93] op_sel_hi:[1,0]
	v_pk_mul_f32 v[82:83], v[82:83], v[88:89] op_sel_hi:[1,0]
	v_pk_mul_f32 v[80:81], v[80:81], v[88:89] op_sel_hi:[1,0]
	v_mul_f32_e32 v88, 0x3fb8aa3b, v90
	v_exp_f32_e32 v88, v88
	s_nop 0
	v_pk_mul_f32 v[90:91], v[86:87], v[88:89] op_sel_hi:[1,0]
	v_pk_mul_f32 v[88:89], v[84:85], v[88:89] op_sel_hi:[1,0]
	s_waitcnt lgkmcnt(5)
	v_mfma_f32_16x16x32_bf16 v[84:87], v[224:227], v[228:231], v[76:79]
	ds_read_b128 v[228:231], v216 offset:34816
	s_nop 2
	s_waitcnt lgkmcnt(5)
	v_mfma_f32_16x16x32_bf16 v[80:83], v[224:227], v[232:235], v[80:83]
	ds_read_b128 v[232:235], v216 offset:37120
	s_waitcnt lgkmcnt(5)
	v_mfma_f32_16x16x32_bf16 v[76:79], v[224:227], v[236:239], v[88:91]
	ds_read_b128 v[236:239], v216 offset:39424
	s_nop 2
	ds_read_b128 v[88:91], v158 offset:53312
	s_waitcnt lgkmcnt(5)
	v_mul_f32_e32 v119, 0x3fb8aa3b, v244
	ds_read_b128 v[244:247], v216 offset:41728
	s_waitcnt lgkmcnt(1)
	v_mfma_f32_16x16x32_bf16 v[76:79], v[88:91], v[240:243], v[76:79]
	ds_read_b128 v[240:243], v216 offset:44032
	v_mfma_f32_16x16x32_bf16 v[72:75], v[224:227], v[248:251], v[72:75]
	ds_read_b128 v[248:251], v216 offset:46336
	ds_read_b128 v[218:221], v217 offset:64832
	s_waitcnt lgkmcnt(0)
	v_mfma_f32_16x16x32_bf16 v[72:75], v[88:91], v[218:221], v[72:75]
	v_exp_f32_e32 v218, v119
	s_nop 0
	v_pk_mul_f32 v[2:3], v[2:3], v[218:219] op_sel_hi:[1,0]
	v_pk_mul_f32 v[0:1], v[0:1], v[218:219] op_sel_hi:[1,0]
	v_pk_mul_f32 v[6:7], v[6:7], v[218:219] op_sel_hi:[1,0]
	v_pk_mul_f32 v[4:5], v[4:5], v[218:219] op_sel_hi:[1,0]
	v_pk_mul_f32 v[10:11], v[10:11], v[218:219] op_sel_hi:[1,0]
	v_pk_mul_f32 v[8:9], v[8:9], v[218:219] op_sel_hi:[1,0]
	v_pk_mul_f32 v[14:15], v[14:15], v[218:219] op_sel_hi:[1,0]
	v_pk_mul_f32 v[12:13], v[12:13], v[218:219] op_sel_hi:[1,0]
	v_pk_mul_f32 v[18:19], v[18:19], v[218:219] op_sel_hi:[1,0]
	v_pk_mul_f32 v[16:17], v[16:17], v[218:219] op_sel_hi:[1,0]
	v_pk_mul_f32 v[22:23], v[22:23], v[218:219] op_sel_hi:[1,0]
	v_pk_mul_f32 v[20:21], v[20:21], v[218:219] op_sel_hi:[1,0]
	v_pk_mul_f32 v[26:27], v[26:27], v[218:219] op_sel_hi:[1,0]
	v_pk_mul_f32 v[24:25], v[24:25], v[218:219] op_sel_hi:[1,0]
	v_pk_mul_f32 v[30:31], v[30:31], v[218:219] op_sel_hi:[1,0]
	v_pk_mul_f32 v[28:29], v[28:29], v[218:219] op_sel_hi:[1,0]
	v_mfma_f32_16x16x32_bf16 v[0:3], v[228:231], v[224:227], v[0:3]
	ds_read_b128 v[228:231], v216 offset:48640
	v_mfma_f32_16x16x32_bf16 v[4:7], v[232:235], v[224:227], v[4:7]
	ds_read_b128 v[232:235], v216 offset:34880
	v_mfma_f32_16x16x32_bf16 v[8:11], v[236:239], v[224:227], v[8:11]
	ds_read_b128 v[236:239], v216 offset:37184
	v_mfma_f32_16x16x32_bf16 v[12:15], v[244:247], v[224:227], v[12:15]
	ds_read_b128 v[244:247], v216 offset:39488
	v_mfma_f32_16x16x32_bf16 v[16:19], v[240:243], v[224:227], v[16:19]
	ds_read_b128 v[240:243], v216 offset:41792
	v_mfma_f32_16x16x32_bf16 v[20:23], v[248:251], v[224:227], v[20:23]
	ds_read_b128 v[248:251], v216 offset:44096
	s_waitcnt lgkmcnt(5)
	v_mfma_f32_16x16x32_bf16 v[24:27], v[228:231], v[224:227], v[24:27]
	ds_read_b128 v[228:231], v216 offset:46400
	ds_read_b128 v[218:221], v216 offset:50944
	s_waitcnt lgkmcnt(0)
	v_mfma_f32_16x16x32_bf16 v[28:31], v[218:221], v[224:227], v[28:31]
	ds_read_b128 v[224:227], v216 offset:48704
	v_mfma_f32_16x16x32_bf16 v[0:3], v[232:235], v[88:91], v[0:3]
	v_mfma_f32_16x16x32_bf16 v[4:7], v[236:239], v[88:91], v[4:7]
	v_mfma_f32_16x16x32_bf16 v[8:11], v[244:247], v[88:91], v[8:11]
	v_mfma_f32_16x16x32_bf16 v[12:15], v[240:243], v[88:91], v[12:15]
	v_mfma_f32_16x16x32_bf16 v[16:19], v[248:251], v[88:91], v[16:19]
	v_mfma_f32_16x16x32_bf16 v[20:23], v[228:231], v[88:91], v[20:23]
	s_waitcnt lgkmcnt(0)
	v_mfma_f32_16x16x32_bf16 v[24:27], v[224:227], v[88:91], v[24:27]
	ds_read_b128 v[92:95], v216 offset:51008
	s_waitcnt lgkmcnt(0)
	v_mfma_f32_16x16x32_bf16 v[28:31], v[92:95], v[88:91], v[28:31]
	s_waitcnt vmcnt(7)
	v_lshlrev_b32_e32 v88, 16, v140
	s_waitcnt vmcnt(6)
	v_lshlrev_b32_e32 v90, 16, v138
	v_and_b32_e32 v89, 0xffff0000, v140
	v_and_b32_e32 v91, 0xffff0000, v138
	v_mul_f32_e32 v92, 0xbfb8aa3b, v90
	v_pk_fma_f32 v[84:85], v[96:97], v[88:89], v[84:85]
	v_mul_f32_e32 v88, 0xbfb8aa3b, v91
	v_exp_f32_e32 v92, v92
	v_exp_f32_e32 v88, v88
	v_add_f32_e32 v92, 1.0, v92
	v_add_f32_e32 v88, 1.0, v88
	v_rcp_f32_e32 v92, v92
	v_rcp_f32_e32 v93, v88
	s_nop 0
	v_pk_mul_f32 v[88:89], v[92:93], v[90:91]
	s_nop 0
	v_pk_mul_f32 v[84:85], v[88:89], v[84:85]
	v_lshlrev_b32_e32 v88, 16, v141
	v_lshlrev_b32_e32 v90, 16, v139
	v_and_b32_e32 v89, 0xffff0000, v141
	v_and_b32_e32 v91, 0xffff0000, v139
	v_mul_f32_e32 v92, 0xbfb8aa3b, v90
	v_pk_fma_f32 v[86:87], v[96:97], v[88:89], v[86:87]
	v_mul_f32_e32 v88, 0xbfb8aa3b, v91
	v_exp_f32_e32 v92, v92
	v_exp_f32_e32 v88, v88
	v_add_f32_e32 v92, 1.0, v92
	v_add_f32_e32 v88, 1.0, v88
	v_rcp_f32_e32 v92, v92
	v_rcp_f32_e32 v93, v88
	s_nop 0
	v_pk_mul_f32 v[88:89], v[92:93], v[90:91]
	s_nop 0
	v_pk_mul_f32 v[86:87], v[88:89], v[86:87]
	v_cvt_pk_bf16_f32 v88, v84, v85
	v_pk_mul_f32 v[84:85], v[84:85], v[84:85]
	v_cvt_pk_bf16_f32 v89, v86, v87
	v_pk_mul_f32 v[86:87], v[86:87], v[86:87]
	v_add_f32_e32 v84, v84, v85
	v_add_f32_e32 v84, v86, v84
	v_add_f32_e32 v84, v87, v84
	ds_bpermute_b32 v85, v159, v84
	v_lshlrev_b64 v[90:91], 12, v[136:137]
	v_lshl_add_u64 v[90:91], s[94:95], 0, v[90:91]
	v_lshl_add_u64 v[90:91], s[0:1], 1, v[90:91]
	v_lshl_add_u64 v[90:91], v[102:103], 1, v[90:91]
	s_waitcnt lgkmcnt(0)
	v_add_f32_e32 v84, v84, v85
	ds_bpermute_b32 v85, v164, v84
	v_add_co_u32_e32 v90, vcc, s14, v90
	s_nop 1
	v_addc_co_u32_e32 v91, vcc, 0, v91, vcc
	global_store_dwordx2 v[90:91], v[88:89], off offset:2560
	s_and_saveexec_b64 s[6:7], s[38:39]
	s_cbranch_execz .LBB0_597
	s_waitcnt lgkmcnt(0)
	v_add_f32_e32 v84, v84, v85
	ds_write_b32 v212, v84

; DI float bflo(unsigned u) { return __uint_as_float(u << 16); }
; DI float bfhi(unsigned u) { return __uint_as_float(u & 0xffff0000u); }
; template <int MODE>
; PH void gemm_phase(const Params& p, int layer) {
;     ...
;                 for (int nt = 0; nt < 4; ++nt) {
;                   const int n = n0 + wn * 64 + nt * 16 + quad * 4;
;                   float4 xr;
;                   if (layer == 0) xr = *(const float4*)(xres + n);
;                   else { const uint2 xb2 = *(const uint2*)(xrb + n); xr = make_float4(bflo(xb2.x), bfhi(xb2.x), bflo(xb2.y), bfhi(xb2.y)); }
;                   float4 o;
;                   o.x = alpha * xr.x + acc[nt][mt][0]; o.y = alpha * xr.y + acc[nt][mt][1];
;                   o.z = alpha * xr.z + acc[nt][mt][2]; o.w = alpha * xr.w + acc[nt][mt][3];
;                   *(float4*)(PRE + (size_t)m * 1024 + n) = o;
;                 }
.LBB0_679:
	s_waitcnt vmcnt(0)
	v_pk_fma_f32 v[96:97], v[96:97], s[70:71], v[32:33] op_sel_hi:[1,0,1]
	v_pk_fma_f32 v[98:99], v[98:99], s[70:71], v[34:35] op_sel_hi:[1,0,1]
	global_store_dwordx4 v[100:101], v[96:99], off offset:192
	.p2align 8
